# prologue embedding loop hand-scheduled: all row loads issued up front, next row prefetched (same arithmetic)
# speedup vs baseline: 1.0185x; 1.0185x over previous
.LBB0_204:
	s_or_b64 exec, exec, s[8:9]
	s_cmpk_gt_i32 s44, 0x47ff
	s_barrier
	s_cbranch_scc1 .LBB0_221
	v_lshlrev_b32_e32 v120, 4, v30
	v_lshlrev_b32_e32 v121, 3, v30
	v_mov_b32_e32 v116, 0x358637bd
	v_mov_b32_e32 v117, 0x260
	s_mov_b32 s3, 0xf800000
	s_lshl_b32 s14, s44, 12
	s_add_u32 s4, s12, s14
	s_addc_u32 s5, s13, 0
	s_add_u32 s22, s16, s14
	s_addc_u32 s23, s17, 0
	s_mov_b64 s[6:7], s[38:39]
	s_add_u32 s8, s38, 0x1000
	s_addc_u32 s9, s39, 0
	s_lshl_b32 s15, s44, 11
	s_add_u32 s10, s48, s15
	s_addc_u32 s11, s49, 0
	s_add_u32 s10, s10, 0x9300000
	s_addc_u32 s11, s11, 0
	s_add_u32 s12, s48, s15
	s_addc_u32 s13, s49, 0
	s_add_u32 s12, s12, 0x1e00000
	s_addc_u32 s13, s13, 0
	s_lshr_b32 s14, s44, 6
	s_lshl_b32 s14, s14, 11
	s_add_u32 s18, s48, s14
	s_addc_u32 s19, s49, 0
	s_add_u32 s18, s18, 0x190000
	s_addc_u32 s19, s19, 0
	s_and_b32 s14, s44, 63
	s_lshl_b32 s14, s14, 11
	s_add_u32 s20, s48, s14
	s_addc_u32 s21, s49, 0
	s_add_u32 s20, s20, 0x190000
	s_addc_u32 s21, s21, 0
	global_load_dwordx4 v[100:103], v120, s[24:25]
	global_load_dwordx4 v[104:107], v120, s[24:25] offset:1024
	global_load_dwordx4 v[108:111], v120, s[24:25] offset:2048
	global_load_dwordx4 v[112:115], v120, s[24:25] offset:3072
	global_load_dwordx4 v[84:87], v120, s[18:19]
	global_load_dwordx4 v[88:91], v120, s[18:19] offset:1024
	global_load_dwordx4 v[92:95], v120, s[20:21]
	global_load_dwordx4 v[96:99], v120, s[20:21] offset:1024
	global_load_dwordx4 v[0:3], v120, s[4:5] nt
	global_load_dwordx4 v[4:7], v120, s[4:5] offset:1024 nt
	global_load_dwordx4 v[8:11], v120, s[4:5] offset:2048 nt
	global_load_dwordx4 v[12:15], v120, s[4:5] offset:3072 nt
	global_load_dwordx4 v[16:19], v120, s[8:9]
	global_load_dwordx4 v[20:23], v120, s[8:9] offset:1024
	global_load_dwordx4 v[24:27], v120, s[8:9] offset:2048
	global_load_dwordx4 v[28:31], v120, s[8:9] offset:3072
	global_load_dwordx4 v[32:35], v120, s[6:7]
	global_load_dwordx4 v[36:39], v120, s[6:7] offset:1024
	global_load_dwordx4 v[40:43], v120, s[6:7] offset:2048
	global_load_dwordx4 v[44:47], v120, s[6:7] offset:3072
	s_add_u32 s4, s4, 0x800000
	s_addc_u32 s5, s5, 0
	s_add_u32 s6, s6, 0x3000
	s_addc_u32 s7, s7, 0
	s_add_u32 s8, s8, 0x3000
	s_addc_u32 s9, s9, 0
	global_load_dwordx4 v[128:131], v120, s[4:5] nt
	global_load_dwordx4 v[132:135], v120, s[4:5] offset:1024 nt
	global_load_dwordx4 v[136:139], v120, s[4:5] offset:2048 nt
	global_load_dwordx4 v[140:143], v120, s[4:5] offset:3072 nt
	global_load_dwordx4 v[144:147], v120, s[8:9]
	global_load_dwordx4 v[148:151], v120, s[8:9] offset:1024
	global_load_dwordx4 v[152:155], v120, s[8:9] offset:2048
	global_load_dwordx4 v[156:159], v120, s[8:9] offset:3072
	global_load_dwordx4 v[160:163], v120, s[6:7]
	global_load_dwordx4 v[164:167], v120, s[6:7] offset:1024
	global_load_dwordx4 v[168:171], v120, s[6:7] offset:2048
	global_load_dwordx4 v[172:175], v120, s[6:7] offset:3072
	s_waitcnt vmcnt(12)
	v_pk_add_f32 v[0:1], v[0:1], v[84:85]
	v_pk_add_f32 v[2:3], v[2:3], v[86:87]
	v_pk_add_f32 v[4:5], v[4:5], v[88:89]
	v_pk_add_f32 v[6:7], v[6:7], v[90:91]
	v_pk_add_f32 v[8:9], v[8:9], v[92:93]
	v_pk_add_f32 v[10:11], v[10:11], v[94:95]
	v_pk_add_f32 v[12:13], v[12:13], v[96:97]
	v_pk_add_f32 v[14:15], v[14:15], v[98:99]
	v_cvt_pk_bf16_f32 v176, v0, v1
	v_cvt_pk_bf16_f32 v177, v2, v3
	global_store_dwordx2 v121, v[176:177], s[10:11]
	v_cvt_pk_bf16_f32 v178, v4, v5
	v_cvt_pk_bf16_f32 v179, v6, v7
	global_store_dwordx2 v121, v[178:179], s[10:11] offset:512
	v_cvt_pk_bf16_f32 v180, v8, v9
	v_cvt_pk_bf16_f32 v181, v10, v11
	global_store_dwordx2 v121, v[180:181], s[10:11] offset:1024
	v_cvt_pk_bf16_f32 v182, v12, v13
	v_cvt_pk_bf16_f32 v183, v14, v15
	global_store_dwordx2 v121, v[182:183], s[10:11] offset:1536
	v_mul_f32_e32 v192, v1, v1
	v_mul_f32_e32 v193, v3, v3
	v_mul_f32_e32 v194, v5, v5
	v_mul_f32_e32 v195, v7, v7
	v_mul_f32_e32 v196, v9, v9
	v_mul_f32_e32 v197, v11, v11
	v_pk_mul_f32 v[198:199], v[14:15], v[14:15]
	v_pk_mul_f32 v[200:201], v[12:13], v[12:13]
	v_fmac_f32_e32 v192, v0, v0
	v_fmac_f32_e32 v193, v2, v2
	v_fmac_f32_e32 v194, v4, v4
	v_fmac_f32_e32 v195, v6, v6
	v_fmac_f32_e32 v196, v8, v8
	v_fmac_f32_e32 v197, v10, v10
	v_add_f32_e32 v202, v201, v200
	v_add_f32_e32 v203, v198, v199
	v_add_f32_e32 v192, v192, v193
	v_add_f32_e32 v193, v194, v195
	v_add_f32_e32 v194, v196, v197
	v_add_f32_e32 v192, v192, v193
	v_add_f32_e32 v202, v202, v203
	v_add_f32_e32 v193, v192, v194
	v_add_f32_e32 v202, v193, v202
	s_nop 1
	v_add_f32_dpp v202, v202, v202 quad_perm:[1,0,3,2] row_mask:0xf bank_mask:0xf bound_ctrl:1
	s_nop 1
	v_add_f32_dpp v202, v202, v202 quad_perm:[2,3,0,1] row_mask:0xf bank_mask:0xf bound_ctrl:1
	s_nop 1
	v_add_f32_dpp v202, v202, v202 row_half_mirror row_mask:0xf bank_mask:0xf bound_ctrl:1
	s_nop 1
	v_add_f32_dpp v202, v202, v202 row_mirror row_mask:0xf bank_mask:0xf bound_ctrl:1
	s_nop 1
	v_readlane_b32 s14, v202, 16
	v_readlane_b32 s15, v202, 48
	v_readlane_b32 s18, v202, 0
	v_readlane_b32 s19, v202, 32
	s_nop 1
	v_mov_b32_e32 v202, s14
	v_mov_b32_e32 v203, s15
	v_pk_add_f32 v[202:203], s[18:19], v[202:203]
	s_nop 0
	v_add_f32_e32 v202, v202, v203
	v_fmamk_f32 v202, v202, 0x3a800000, v116
	v_mul_f32_e32 v203, 0x4f800000, v202
	v_cmp_gt_f32_e32 vcc, s3, v202
	s_nop 1
	v_cndmask_b32_e32 v202, v202, v203, vcc
	v_sqrt_f32_e32 v203, v202
	s_nop 0
	v_add_u32_e32 v204, -1, v203
	v_add_u32_e32 v205, 1, v203
	v_fma_f32 v206, -v204, v203, v202
	v_fma_f32 v207, -v205, v203, v202
	v_cmp_ge_f32_e64 s[20:21], 0, v206
	s_nop 1
	v_cndmask_b32_e64 v203, v203, v204, s[20:21]
	v_cmp_lt_f32_e64 s[20:21], 0, v207
	s_nop 1
	v_cndmask_b32_e64 v203, v203, v205, s[20:21]
	v_mul_f32_e32 v204, 0x37800000, v203
	v_cndmask_b32_e32 v203, v203, v204, vcc
	v_cmp_class_f32_e32 vcc, v202, v117
	s_nop 1
	v_cndmask_b32_e32 v204, v203, v202, vcc
	v_div_scale_f32 v205, s[20:21], v204, v204, 1.0
	v_rcp_f32_e32 v206, v205
	v_div_scale_f32 v207, vcc, 1.0, v204, 1.0
	s_nop 0
	v_fma_f32 v208, -v205, v206, 1.0
	v_fmac_f32_e32 v206, v208, v206
	v_mul_f32_e32 v208, v207, v206
	v_fma_f32 v209, -v205, v208, v207
	v_fmac_f32_e32 v208, v209, v206
	v_fma_f32 v205, -v205, v208, v207
	v_div_fmas_f32 v205, v205, v206, v208
	v_div_fixup_f32 v210, v205, v204, 1.0
	v_pk_add_f32 v[16:17], v[16:17], 1.0 op_sel_hi:[1,0]
	v_pk_add_f32 v[18:19], v[18:19], 1.0 op_sel_hi:[1,0]
	v_pk_mul_f32 v[16:17], v[100:101], v[16:17]
	v_pk_mul_f32 v[18:19], v[102:103], v[18:19]
	v_pk_mul_f32 v[0:1], v[0:1], v[210:211] op_sel_hi:[1,0]
	v_pk_mul_f32 v[2:3], v[2:3], v[210:211] op_sel_hi:[1,0]
	v_pk_fma_f32 v[0:1], v[16:17], v[0:1], v[32:33]
	v_pk_fma_f32 v[2:3], v[18:19], v[2:3], v[34:35]
	v_cvt_pk_bf16_f32 v184, v0, v1
	v_cvt_pk_bf16_f32 v185, v2, v3
	global_store_dwordx2 v121, v[184:185], s[12:13]
	v_pk_add_f32 v[20:21], v[20:21], 1.0 op_sel_hi:[1,0]
	v_pk_add_f32 v[22:23], v[22:23], 1.0 op_sel_hi:[1,0]
	v_pk_mul_f32 v[20:21], v[104:105], v[20:21]
	v_pk_mul_f32 v[22:23], v[106:107], v[22:23]
	v_pk_mul_f32 v[4:5], v[4:5], v[210:211] op_sel_hi:[1,0]
	v_pk_mul_f32 v[6:7], v[6:7], v[210:211] op_sel_hi:[1,0]
	v_pk_fma_f32 v[4:5], v[20:21], v[4:5], v[36:37]
	v_pk_fma_f32 v[6:7], v[22:23], v[6:7], v[38:39]
	v_cvt_pk_bf16_f32 v186, v4, v5
	v_cvt_pk_bf16_f32 v187, v6, v7
	global_store_dwordx2 v121, v[186:187], s[12:13] offset:512
	v_pk_add_f32 v[24:25], v[24:25], 1.0 op_sel_hi:[1,0]
	v_pk_add_f32 v[26:27], v[26:27], 1.0 op_sel_hi:[1,0]
	v_pk_mul_f32 v[24:25], v[108:109], v[24:25]
	v_pk_mul_f32 v[26:27], v[110:111], v[26:27]
	v_pk_mul_f32 v[8:9], v[8:9], v[210:211] op_sel_hi:[1,0]
	v_pk_mul_f32 v[10:11], v[10:11], v[210:211] op_sel_hi:[1,0]
	v_pk_fma_f32 v[8:9], v[24:25], v[8:9], v[40:41]
	v_pk_fma_f32 v[10:11], v[26:27], v[10:11], v[42:43]
	v_cvt_pk_bf16_f32 v188, v8, v9
	v_cvt_pk_bf16_f32 v189, v10, v11
	global_store_dwordx2 v121, v[188:189], s[12:13] offset:1024
	v_pk_add_f32 v[28:29], v[28:29], 1.0 op_sel_hi:[1,0]
	v_pk_add_f32 v[30:31], v[30:31], 1.0 op_sel_hi:[1,0]
	v_pk_mul_f32 v[28:29], v[112:113], v[28:29]
	v_pk_mul_f32 v[30:31], v[114:115], v[30:31]
	v_pk_mul_f32 v[12:13], v[12:13], v[210:211] op_sel_hi:[1,0]
	v_pk_mul_f32 v[14:15], v[14:15], v[210:211] op_sel_hi:[1,0]
	v_pk_fma_f32 v[12:13], v[28:29], v[12:13], v[44:45]
	v_pk_fma_f32 v[14:15], v[30:31], v[14:15], v[46:47]
	v_cvt_pk_bf16_f32 v190, v12, v13
	v_cvt_pk_bf16_f32 v191, v14, v15
	global_store_dwordx2 v121, v[190:191], s[12:13] offset:1536
	s_add_u32 s10, s10, 0x400000
	s_addc_u32 s11, s11, 0
	s_add_u32 s12, s12, 0x400000
	s_addc_u32 s13, s13, 0
	s_add_u32 s4, s4, 0x800000
	s_addc_u32 s5, s5, 0
	s_add_u32 s6, s6, 0x3000
	s_addc_u32 s7, s7, 0
	s_add_u32 s8, s8, 0x3000
	s_addc_u32 s9, s9, 0
	global_load_dwordx4 v[0:3], v120, s[4:5] nt
	global_load_dwordx4 v[4:7], v120, s[4:5] offset:1024 nt
	global_load_dwordx4 v[8:11], v120, s[4:5] offset:2048 nt
	global_load_dwordx4 v[12:15], v120, s[4:5] offset:3072 nt
	global_load_dwordx4 v[16:19], v120, s[8:9]
	global_load_dwordx4 v[20:23], v120, s[8:9] offset:1024
	global_load_dwordx4 v[24:27], v120, s[8:9] offset:2048
	global_load_dwordx4 v[28:31], v120, s[8:9] offset:3072
	global_load_dwordx4 v[32:35], v120, s[6:7]
	global_load_dwordx4 v[36:39], v120, s[6:7] offset:1024
	global_load_dwordx4 v[40:43], v120, s[6:7] offset:2048
	global_load_dwordx4 v[44:47], v120, s[6:7] offset:3072
	s_waitcnt vmcnt(20)
	v_pk_add_f32 v[128:129], v[128:129], v[84:85]
	v_pk_add_f32 v[130:131], v[130:131], v[86:87]
	v_pk_add_f32 v[132:133], v[132:133], v[88:89]
	v_pk_add_f32 v[134:135], v[134:135], v[90:91]
	v_pk_add_f32 v[136:137], v[136:137], v[92:93]
	v_pk_add_f32 v[138:139], v[138:139], v[94:95]
	v_pk_add_f32 v[140:141], v[140:141], v[96:97]
	v_pk_add_f32 v[142:143], v[142:143], v[98:99]
	v_cvt_pk_bf16_f32 v176, v128, v129
	v_cvt_pk_bf16_f32 v177, v130, v131
	global_store_dwordx2 v121, v[176:177], s[10:11]
	v_cvt_pk_bf16_f32 v178, v132, v133
	v_cvt_pk_bf16_f32 v179, v134, v135
	global_store_dwordx2 v121, v[178:179], s[10:11] offset:512
	v_cvt_pk_bf16_f32 v180, v136, v137
	v_cvt_pk_bf16_f32 v181, v138, v139
	global_store_dwordx2 v121, v[180:181], s[10:11] offset:1024
	v_cvt_pk_bf16_f32 v182, v140, v141
	v_cvt_pk_bf16_f32 v183, v142, v143
	global_store_dwordx2 v121, v[182:183], s[10:11] offset:1536
	v_mul_f32_e32 v192, v129, v129
	v_mul_f32_e32 v193, v131, v131
	v_mul_f32_e32 v194, v133, v133
	v_mul_f32_e32 v195, v135, v135
	v_mul_f32_e32 v196, v137, v137
	v_mul_f32_e32 v197, v139, v139
	v_pk_mul_f32 v[198:199], v[142:143], v[142:143]
	v_pk_mul_f32 v[200:201], v[140:141], v[140:141]
	v_fmac_f32_e32 v192, v128, v128
	v_fmac_f32_e32 v193, v130, v130
	v_fmac_f32_e32 v194, v132, v132
	v_fmac_f32_e32 v195, v134, v134
	v_fmac_f32_e32 v196, v136, v136
	v_fmac_f32_e32 v197, v138, v138
	v_add_f32_e32 v202, v201, v200
	v_add_f32_e32 v203, v198, v199
	v_add_f32_e32 v192, v192, v193
	v_add_f32_e32 v193, v194, v195
	v_add_f32_e32 v194, v196, v197
	v_add_f32_e32 v192, v192, v193
	v_add_f32_e32 v202, v202, v203
	v_add_f32_e32 v193, v192, v194
	v_add_f32_e32 v202, v193, v202
	s_nop 1
	v_add_f32_dpp v202, v202, v202 quad_perm:[1,0,3,2] row_mask:0xf bank_mask:0xf bound_ctrl:1
	s_nop 1
	v_add_f32_dpp v202, v202, v202 quad_perm:[2,3,0,1] row_mask:0xf bank_mask:0xf bound_ctrl:1
	s_nop 1
	v_add_f32_dpp v202, v202, v202 row_half_mirror row_mask:0xf bank_mask:0xf bound_ctrl:1
	s_nop 1
	v_add_f32_dpp v202, v202, v202 row_mirror row_mask:0xf bank_mask:0xf bound_ctrl:1
	s_nop 1
	v_readlane_b32 s14, v202, 16
	v_readlane_b32 s15, v202, 48
	v_readlane_b32 s18, v202, 0
	v_readlane_b32 s19, v202, 32
	s_nop 1
	v_mov_b32_e32 v202, s14
	v_mov_b32_e32 v203, s15
	v_pk_add_f32 v[202:203], s[18:19], v[202:203]
	s_nop 0
	v_add_f32_e32 v202, v202, v203
	v_fmamk_f32 v202, v202, 0x3a800000, v116
	v_mul_f32_e32 v203, 0x4f800000, v202
	v_cmp_gt_f32_e32 vcc, s3, v202
	s_nop 1
	v_cndmask_b32_e32 v202, v202, v203, vcc
	v_sqrt_f32_e32 v203, v202
	s_nop 0
	v_add_u32_e32 v204, -1, v203
	v_add_u32_e32 v205, 1, v203
	v_fma_f32 v206, -v204, v203, v202
	v_fma_f32 v207, -v205, v203, v202
	v_cmp_ge_f32_e64 s[20:21], 0, v206
	s_nop 1
	v_cndmask_b32_e64 v203, v203, v204, s[20:21]
	v_cmp_lt_f32_e64 s[20:21], 0, v207
	s_nop 1
	v_cndmask_b32_e64 v203, v203, v205, s[20:21]
	v_mul_f32_e32 v204, 0x37800000, v203
	v_cndmask_b32_e32 v203, v203, v204, vcc
	v_cmp_class_f32_e32 vcc, v202, v117
	s_nop 1
	v_cndmask_b32_e32 v204, v203, v202, vcc
	v_div_scale_f32 v205, s[20:21], v204, v204, 1.0
	v_rcp_f32_e32 v206, v205
	v_div_scale_f32 v207, vcc, 1.0, v204, 1.0
	s_nop 0
	v_fma_f32 v208, -v205, v206, 1.0
	v_fmac_f32_e32 v206, v208, v206
	v_mul_f32_e32 v208, v207, v206
	v_fma_f32 v209, -v205, v208, v207
	v_fmac_f32_e32 v208, v209, v206
	v_fma_f32 v205, -v205, v208, v207
	v_div_fmas_f32 v205, v205, v206, v208
	v_div_fixup_f32 v210, v205, v204, 1.0
	v_pk_add_f32 v[144:145], v[144:145], 1.0 op_sel_hi:[1,0]
	v_pk_add_f32 v[146:147], v[146:147], 1.0 op_sel_hi:[1,0]
	v_pk_mul_f32 v[144:145], v[100:101], v[144:145]
	v_pk_mul_f32 v[146:147], v[102:103], v[146:147]
	v_pk_mul_f32 v[128:129], v[128:129], v[210:211] op_sel_hi:[1,0]
	v_pk_mul_f32 v[130:131], v[130:131], v[210:211] op_sel_hi:[1,0]
	v_pk_fma_f32 v[128:129], v[144:145], v[128:129], v[160:161]
	v_pk_fma_f32 v[130:131], v[146:147], v[130:131], v[162:163]
	v_cvt_pk_bf16_f32 v184, v128, v129
	v_cvt_pk_bf16_f32 v185, v130, v131
	global_store_dwordx2 v121, v[184:185], s[12:13]
	v_pk_add_f32 v[148:149], v[148:149], 1.0 op_sel_hi:[1,0]
	v_pk_add_f32 v[150:151], v[150:151], 1.0 op_sel_hi:[1,0]
	v_pk_mul_f32 v[148:149], v[104:105], v[148:149]
	v_pk_mul_f32 v[150:151], v[106:107], v[150:151]
	v_pk_mul_f32 v[132:133], v[132:133], v[210:211] op_sel_hi:[1,0]
	v_pk_mul_f32 v[134:135], v[134:135], v[210:211] op_sel_hi:[1,0]
	v_pk_fma_f32 v[132:133], v[148:149], v[132:133], v[164:165]
	v_pk_fma_f32 v[134:135], v[150:151], v[134:135], v[166:167]
	v_cvt_pk_bf16_f32 v186, v132, v133
	v_cvt_pk_bf16_f32 v187, v134, v135
	global_store_dwordx2 v121, v[186:187], s[12:13] offset:512
	v_pk_add_f32 v[152:153], v[152:153], 1.0 op_sel_hi:[1,0]
	v_pk_add_f32 v[154:155], v[154:155], 1.0 op_sel_hi:[1,0]
	v_pk_mul_f32 v[152:153], v[108:109], v[152:153]
	v_pk_mul_f32 v[154:155], v[110:111], v[154:155]
	v_pk_mul_f32 v[136:137], v[136:137], v[210:211] op_sel_hi:[1,0]
	v_pk_mul_f32 v[138:139], v[138:139], v[210:211] op_sel_hi:[1,0]
	v_pk_fma_f32 v[136:137], v[152:153], v[136:137], v[168:169]
	v_pk_fma_f32 v[138:139], v[154:155], v[138:139], v[170:171]
	v_cvt_pk_bf16_f32 v188, v136, v137
	v_cvt_pk_bf16_f32 v189, v138, v139
	global_store_dwordx2 v121, v[188:189], s[12:13] offset:1024
	v_pk_add_f32 v[156:157], v[156:157], 1.0 op_sel_hi:[1,0]
	v_pk_add_f32 v[158:159], v[158:159], 1.0 op_sel_hi:[1,0]
	v_pk_mul_f32 v[156:157], v[112:113], v[156:157]
	v_pk_mul_f32 v[158:159], v[114:115], v[158:159]
	v_pk_mul_f32 v[140:141], v[140:141], v[210:211] op_sel_hi:[1,0]
	v_pk_mul_f32 v[142:143], v[142:143], v[210:211] op_sel_hi:[1,0]
	v_pk_fma_f32 v[140:141], v[156:157], v[140:141], v[172:173]
	v_pk_fma_f32 v[142:143], v[158:159], v[142:143], v[174:175]
	v_cvt_pk_bf16_f32 v190, v140, v141
	v_cvt_pk_bf16_f32 v191, v142, v143
	global_store_dwordx2 v121, v[190:191], s[12:13] offset:1536
	s_add_u32 s10, s10, 0x400000
	s_addc_u32 s11, s11, 0
	s_add_u32 s12, s12, 0x400000
	s_addc_u32 s13, s13, 0
	s_add_u32 s4, s4, 0x800000
	s_addc_u32 s5, s5, 0
	s_add_u32 s6, s6, 0x3000
	s_addc_u32 s7, s7, 0
	s_add_u32 s8, s8, 0x3000
	s_addc_u32 s9, s9, 0
	global_load_dwordx4 v[128:131], v120, s[4:5] nt
	global_load_dwordx4 v[132:135], v120, s[4:5] offset:1024 nt
	global_load_dwordx4 v[136:139], v120, s[4:5] offset:2048 nt
	global_load_dwordx4 v[140:143], v120, s[4:5] offset:3072 nt
	global_load_dwordx4 v[144:147], v120, s[8:9]
	global_load_dwordx4 v[148:151], v120, s[8:9] offset:1024
	global_load_dwordx4 v[152:155], v120, s[8:9] offset:2048
	global_load_dwordx4 v[156:159], v120, s[8:9] offset:3072
	global_load_dwordx4 v[160:163], v120, s[6:7]
	global_load_dwordx4 v[164:167], v120, s[6:7] offset:1024
	global_load_dwordx4 v[168:171], v120, s[6:7] offset:2048
	global_load_dwordx4 v[172:175], v120, s[6:7] offset:3072
	s_waitcnt vmcnt(20)
	v_pk_add_f32 v[0:1], v[0:1], v[84:85]
	v_pk_add_f32 v[2:3], v[2:3], v[86:87]
	v_pk_add_f32 v[4:5], v[4:5], v[88:89]
	v_pk_add_f32 v[6:7], v[6:7], v[90:91]
	v_pk_add_f32 v[8:9], v[8:9], v[92:93]
	v_pk_add_f32 v[10:11], v[10:11], v[94:95]
	v_pk_add_f32 v[12:13], v[12:13], v[96:97]
	v_pk_add_f32 v[14:15], v[14:15], v[98:99]
	v_cvt_pk_bf16_f32 v176, v0, v1
	v_cvt_pk_bf16_f32 v177, v2, v3
	global_store_dwordx2 v121, v[176:177], s[10:11]
	v_cvt_pk_bf16_f32 v178, v4, v5
	v_cvt_pk_bf16_f32 v179, v6, v7
	global_store_dwordx2 v121, v[178:179], s[10:11] offset:512
	v_cvt_pk_bf16_f32 v180, v8, v9
	v_cvt_pk_bf16_f32 v181, v10, v11
	global_store_dwordx2 v121, v[180:181], s[10:11] offset:1024
	v_cvt_pk_bf16_f32 v182, v12, v13
	v_cvt_pk_bf16_f32 v183, v14, v15
	global_store_dwordx2 v121, v[182:183], s[10:11] offset:1536
	v_mul_f32_e32 v192, v1, v1
	v_mul_f32_e32 v193, v3, v3
	v_mul_f32_e32 v194, v5, v5
	v_mul_f32_e32 v195, v7, v7
	v_mul_f32_e32 v196, v9, v9
	v_mul_f32_e32 v197, v11, v11
	v_pk_mul_f32 v[198:199], v[14:15], v[14:15]
	v_pk_mul_f32 v[200:201], v[12:13], v[12:13]
	v_fmac_f32_e32 v192, v0, v0
	v_fmac_f32_e32 v193, v2, v2
	v_fmac_f32_e32 v194, v4, v4
	v_fmac_f32_e32 v195, v6, v6
	v_fmac_f32_e32 v196, v8, v8
	v_fmac_f32_e32 v197, v10, v10
	v_add_f32_e32 v202, v201, v200
	v_add_f32_e32 v203, v198, v199
	v_add_f32_e32 v192, v192, v193
	v_add_f32_e32 v193, v194, v195
	v_add_f32_e32 v194, v196, v197
	v_add_f32_e32 v192, v192, v193
	v_add_f32_e32 v202, v202, v203
	v_add_f32_e32 v193, v192, v194
	v_add_f32_e32 v202, v193, v202
	s_nop 1
	v_add_f32_dpp v202, v202, v202 quad_perm:[1,0,3,2] row_mask:0xf bank_mask:0xf bound_ctrl:1
	s_nop 1
	v_add_f32_dpp v202, v202, v202 quad_perm:[2,3,0,1] row_mask:0xf bank_mask:0xf bound_ctrl:1
	s_nop 1
	v_add_f32_dpp v202, v202, v202 row_half_mirror row_mask:0xf bank_mask:0xf bound_ctrl:1
	s_nop 1
	v_add_f32_dpp v202, v202, v202 row_mirror row_mask:0xf bank_mask:0xf bound_ctrl:1
	s_nop 1
	v_readlane_b32 s14, v202, 16
	v_readlane_b32 s15, v202, 48
	v_readlane_b32 s18, v202, 0
	v_readlane_b32 s19, v202, 32
	s_nop 1
	v_mov_b32_e32 v202, s14
	v_mov_b32_e32 v203, s15
	v_pk_add_f32 v[202:203], s[18:19], v[202:203]
	s_nop 0
	v_add_f32_e32 v202, v202, v203
	v_fmamk_f32 v202, v202, 0x3a800000, v116
	v_mul_f32_e32 v203, 0x4f800000, v202
	v_cmp_gt_f32_e32 vcc, s3, v202
	s_nop 1
	v_cndmask_b32_e32 v202, v202, v203, vcc
	v_sqrt_f32_e32 v203, v202
	s_nop 0
	v_add_u32_e32 v204, -1, v203
	v_add_u32_e32 v205, 1, v203
	v_fma_f32 v206, -v204, v203, v202
	v_fma_f32 v207, -v205, v203, v202
	v_cmp_ge_f32_e64 s[20:21], 0, v206
	s_nop 1
	v_cndmask_b32_e64 v203, v203, v204, s[20:21]
	v_cmp_lt_f32_e64 s[20:21], 0, v207
	s_nop 1
	v_cndmask_b32_e64 v203, v203, v205, s[20:21]
	v_mul_f32_e32 v204, 0x37800000, v203
	v_cndmask_b32_e32 v203, v203, v204, vcc
	v_cmp_class_f32_e32 vcc, v202, v117
	s_nop 1
	v_cndmask_b32_e32 v204, v203, v202, vcc
	v_div_scale_f32 v205, s[20:21], v204, v204, 1.0
	v_rcp_f32_e32 v206, v205
	v_div_scale_f32 v207, vcc, 1.0, v204, 1.0
	s_nop 0
	v_fma_f32 v208, -v205, v206, 1.0
	v_fmac_f32_e32 v206, v208, v206
	v_mul_f32_e32 v208, v207, v206
	v_fma_f32 v209, -v205, v208, v207
	v_fmac_f32_e32 v208, v209, v206
	v_fma_f32 v205, -v205, v208, v207
	v_div_fmas_f32 v205, v205, v206, v208
	v_div_fixup_f32 v210, v205, v204, 1.0
	v_pk_add_f32 v[16:17], v[16:17], 1.0 op_sel_hi:[1,0]
	v_pk_add_f32 v[18:19], v[18:19], 1.0 op_sel_hi:[1,0]
	v_pk_mul_f32 v[16:17], v[100:101], v[16:17]
	v_pk_mul_f32 v[18:19], v[102:103], v[18:19]
	v_pk_mul_f32 v[0:1], v[0:1], v[210:211] op_sel_hi:[1,0]
	v_pk_mul_f32 v[2:3], v[2:3], v[210:211] op_sel_hi:[1,0]
	v_pk_fma_f32 v[0:1], v[16:17], v[0:1], v[32:33]
	v_pk_fma_f32 v[2:3], v[18:19], v[2:3], v[34:35]
	v_cvt_pk_bf16_f32 v184, v0, v1
	v_cvt_pk_bf16_f32 v185, v2, v3
	global_store_dwordx2 v121, v[184:185], s[12:13]
	v_pk_add_f32 v[20:21], v[20:21], 1.0 op_sel_hi:[1,0]
	v_pk_add_f32 v[22:23], v[22:23], 1.0 op_sel_hi:[1,0]
	v_pk_mul_f32 v[20:21], v[104:105], v[20:21]
	v_pk_mul_f32 v[22:23], v[106:107], v[22:23]
	v_pk_mul_f32 v[4:5], v[4:5], v[210:211] op_sel_hi:[1,0]
	v_pk_mul_f32 v[6:7], v[6:7], v[210:211] op_sel_hi:[1,0]
	v_pk_fma_f32 v[4:5], v[20:21], v[4:5], v[36:37]
	v_pk_fma_f32 v[6:7], v[22:23], v[6:7], v[38:39]
	v_cvt_pk_bf16_f32 v186, v4, v5
	v_cvt_pk_bf16_f32 v187, v6, v7
	global_store_dwordx2 v121, v[186:187], s[12:13] offset:512
	v_pk_add_f32 v[24:25], v[24:25], 1.0 op_sel_hi:[1,0]
	v_pk_add_f32 v[26:27], v[26:27], 1.0 op_sel_hi:[1,0]
	v_pk_mul_f32 v[24:25], v[108:109], v[24:25]
	v_pk_mul_f32 v[26:27], v[110:111], v[26:27]
	v_pk_mul_f32 v[8:9], v[8:9], v[210:211] op_sel_hi:[1,0]
	v_pk_mul_f32 v[10:11], v[10:11], v[210:211] op_sel_hi:[1,0]
	v_pk_fma_f32 v[8:9], v[24:25], v[8:9], v[40:41]
	v_pk_fma_f32 v[10:11], v[26:27], v[10:11], v[42:43]
	v_cvt_pk_bf16_f32 v188, v8, v9
	v_cvt_pk_bf16_f32 v189, v10, v11
	global_store_dwordx2 v121, v[188:189], s[12:13] offset:1024
	v_pk_add_f32 v[28:29], v[28:29], 1.0 op_sel_hi:[1,0]
	v_pk_add_f32 v[30:31], v[30:31], 1.0 op_sel_hi:[1,0]
	v_pk_mul_f32 v[28:29], v[112:113], v[28:29]
	v_pk_mul_f32 v[30:31], v[114:115], v[30:31]
	v_pk_mul_f32 v[12:13], v[12:13], v[210:211] op_sel_hi:[1,0]
	v_pk_mul_f32 v[14:15], v[14:15], v[210:211] op_sel_hi:[1,0]
	v_pk_fma_f32 v[12:13], v[28:29], v[12:13], v[44:45]
	v_pk_fma_f32 v[14:15], v[30:31], v[14:15], v[46:47]
	v_cvt_pk_bf16_f32 v190, v12, v13
	v_cvt_pk_bf16_f32 v191, v14, v15
	global_store_dwordx2 v121, v[190:191], s[12:13] offset:1536
	s_add_u32 s10, s10, 0x400000
	s_addc_u32 s11, s11, 0
	s_add_u32 s12, s12, 0x400000
	s_addc_u32 s13, s13, 0
	s_add_u32 s4, s4, 0x800000
	s_addc_u32 s5, s5, 0
	s_add_u32 s6, s6, 0x3000
	s_addc_u32 s7, s7, 0
	s_add_u32 s8, s8, 0x3000
	s_addc_u32 s9, s9, 0
	global_load_dwordx4 v[0:3], v120, s[4:5] nt
	global_load_dwordx4 v[4:7], v120, s[4:5] offset:1024 nt
	global_load_dwordx4 v[8:11], v120, s[4:5] offset:2048 nt
	global_load_dwordx4 v[12:15], v120, s[4:5] offset:3072 nt
	global_load_dwordx4 v[16:19], v120, s[8:9]
	global_load_dwordx4 v[20:23], v120, s[8:9] offset:1024
	global_load_dwordx4 v[24:27], v120, s[8:9] offset:2048
	global_load_dwordx4 v[28:31], v120, s[8:9] offset:3072
	global_load_dwordx4 v[32:35], v120, s[6:7]
	global_load_dwordx4 v[36:39], v120, s[6:7] offset:1024
	global_load_dwordx4 v[40:43], v120, s[6:7] offset:2048
	global_load_dwordx4 v[44:47], v120, s[6:7] offset:3072
	s_waitcnt vmcnt(20)
	v_pk_add_f32 v[128:129], v[128:129], v[84:85]
	v_pk_add_f32 v[130:131], v[130:131], v[86:87]
	v_pk_add_f32 v[132:133], v[132:133], v[88:89]
	v_pk_add_f32 v[134:135], v[134:135], v[90:91]
	v_pk_add_f32 v[136:137], v[136:137], v[92:93]
	v_pk_add_f32 v[138:139], v[138:139], v[94:95]
	v_pk_add_f32 v[140:141], v[140:141], v[96:97]
	v_pk_add_f32 v[142:143], v[142:143], v[98:99]
	v_cvt_pk_bf16_f32 v176, v128, v129
	v_cvt_pk_bf16_f32 v177, v130, v131
	global_store_dwordx2 v121, v[176:177], s[10:11]
	v_cvt_pk_bf16_f32 v178, v132, v133
	v_cvt_pk_bf16_f32 v179, v134, v135
	global_store_dwordx2 v121, v[178:179], s[10:11] offset:512
	v_cvt_pk_bf16_f32 v180, v136, v137
	v_cvt_pk_bf16_f32 v181, v138, v139
	global_store_dwordx2 v121, v[180:181], s[10:11] offset:1024
	v_cvt_pk_bf16_f32 v182, v140, v141
	v_cvt_pk_bf16_f32 v183, v142, v143
	global_store_dwordx2 v121, v[182:183], s[10:11] offset:1536
	v_mul_f32_e32 v192, v129, v129
	v_mul_f32_e32 v193, v131, v131
	v_mul_f32_e32 v194, v133, v133
	v_mul_f32_e32 v195, v135, v135
	v_mul_f32_e32 v196, v137, v137
	v_mul_f32_e32 v197, v139, v139
	v_pk_mul_f32 v[198:199], v[142:143], v[142:143]
	v_pk_mul_f32 v[200:201], v[140:141], v[140:141]
	v_fmac_f32_e32 v192, v128, v128
	v_fmac_f32_e32 v193, v130, v130
	v_fmac_f32_e32 v194, v132, v132
	v_fmac_f32_e32 v195, v134, v134
	v_fmac_f32_e32 v196, v136, v136
	v_fmac_f32_e32 v197, v138, v138
	v_add_f32_e32 v202, v201, v200
	v_add_f32_e32 v203, v198, v199
	v_add_f32_e32 v192, v192, v193
	v_add_f32_e32 v193, v194, v195
	v_add_f32_e32 v194, v196, v197
	v_add_f32_e32 v192, v192, v193
	v_add_f32_e32 v202, v202, v203
	v_add_f32_e32 v193, v192, v194
	v_add_f32_e32 v202, v193, v202
	s_nop 1
	v_add_f32_dpp v202, v202, v202 quad_perm:[1,0,3,2] row_mask:0xf bank_mask:0xf bound_ctrl:1
	s_nop 1
	v_add_f32_dpp v202, v202, v202 quad_perm:[2,3,0,1] row_mask:0xf bank_mask:0xf bound_ctrl:1
	s_nop 1
	v_add_f32_dpp v202, v202, v202 row_half_mirror row_mask:0xf bank_mask:0xf bound_ctrl:1
	s_nop 1
	v_add_f32_dpp v202, v202, v202 row_mirror row_mask:0xf bank_mask:0xf bound_ctrl:1
	s_nop 1
	v_readlane_b32 s14, v202, 16
	v_readlane_b32 s15, v202, 48
	v_readlane_b32 s18, v202, 0
	v_readlane_b32 s19, v202, 32
	s_nop 1
	v_mov_b32_e32 v202, s14
	v_mov_b32_e32 v203, s15
	v_pk_add_f32 v[202:203], s[18:19], v[202:203]
	s_nop 0
	v_add_f32_e32 v202, v202, v203
	v_fmamk_f32 v202, v202, 0x3a800000, v116
	v_mul_f32_e32 v203, 0x4f800000, v202
	v_cmp_gt_f32_e32 vcc, s3, v202
	s_nop 1
	v_cndmask_b32_e32 v202, v202, v203, vcc
	v_sqrt_f32_e32 v203, v202
	s_nop 0
	v_add_u32_e32 v204, -1, v203
	v_add_u32_e32 v205, 1, v203
	v_fma_f32 v206, -v204, v203, v202
	v_fma_f32 v207, -v205, v203, v202
	v_cmp_ge_f32_e64 s[20:21], 0, v206
	s_nop 1
	v_cndmask_b32_e64 v203, v203, v204, s[20:21]
	v_cmp_lt_f32_e64 s[20:21], 0, v207
	s_nop 1
	v_cndmask_b32_e64 v203, v203, v205, s[20:21]
	v_mul_f32_e32 v204, 0x37800000, v203
	v_cndmask_b32_e32 v203, v203, v204, vcc
	v_cmp_class_f32_e32 vcc, v202, v117
	s_nop 1
	v_cndmask_b32_e32 v204, v203, v202, vcc
	v_div_scale_f32 v205, s[20:21], v204, v204, 1.0
	v_rcp_f32_e32 v206, v205
	v_div_scale_f32 v207, vcc, 1.0, v204, 1.0
	s_nop 0
	v_fma_f32 v208, -v205, v206, 1.0
	v_fmac_f32_e32 v206, v208, v206
	v_mul_f32_e32 v208, v207, v206
	v_fma_f32 v209, -v205, v208, v207
	v_fmac_f32_e32 v208, v209, v206
	v_fma_f32 v205, -v205, v208, v207
	v_div_fmas_f32 v205, v205, v206, v208
	v_div_fixup_f32 v210, v205, v204, 1.0
	v_pk_add_f32 v[144:145], v[144:145], 1.0 op_sel_hi:[1,0]
	v_pk_add_f32 v[146:147], v[146:147], 1.0 op_sel_hi:[1,0]
	v_pk_mul_f32 v[144:145], v[100:101], v[144:145]
	v_pk_mul_f32 v[146:147], v[102:103], v[146:147]
	v_pk_mul_f32 v[128:129], v[128:129], v[210:211] op_sel_hi:[1,0]
	v_pk_mul_f32 v[130:131], v[130:131], v[210:211] op_sel_hi:[1,0]
	v_pk_fma_f32 v[128:129], v[144:145], v[128:129], v[160:161]
	v_pk_fma_f32 v[130:131], v[146:147], v[130:131], v[162:163]
	v_cvt_pk_bf16_f32 v184, v128, v129
	v_cvt_pk_bf16_f32 v185, v130, v131
	global_store_dwordx2 v121, v[184:185], s[12:13]
	v_pk_add_f32 v[148:149], v[148:149], 1.0 op_sel_hi:[1,0]
	v_pk_add_f32 v[150:151], v[150:151], 1.0 op_sel_hi:[1,0]
	v_pk_mul_f32 v[148:149], v[104:105], v[148:149]
	v_pk_mul_f32 v[150:151], v[106:107], v[150:151]
	v_pk_mul_f32 v[132:133], v[132:133], v[210:211] op_sel_hi:[1,0]
	v_pk_mul_f32 v[134:135], v[134:135], v[210:211] op_sel_hi:[1,0]
	v_pk_fma_f32 v[132:133], v[148:149], v[132:133], v[164:165]
	v_pk_fma_f32 v[134:135], v[150:151], v[134:135], v[166:167]
	v_cvt_pk_bf16_f32 v186, v132, v133
	v_cvt_pk_bf16_f32 v187, v134, v135
	global_store_dwordx2 v121, v[186:187], s[12:13] offset:512
	v_pk_add_f32 v[152:153], v[152:153], 1.0 op_sel_hi:[1,0]
	v_pk_add_f32 v[154:155], v[154:155], 1.0 op_sel_hi:[1,0]
	v_pk_mul_f32 v[152:153], v[108:109], v[152:153]
	v_pk_mul_f32 v[154:155], v[110:111], v[154:155]
	v_pk_mul_f32 v[136:137], v[136:137], v[210:211] op_sel_hi:[1,0]
	v_pk_mul_f32 v[138:139], v[138:139], v[210:211] op_sel_hi:[1,0]
	v_pk_fma_f32 v[136:137], v[152:153], v[136:137], v[168:169]
	v_pk_fma_f32 v[138:139], v[154:155], v[138:139], v[170:171]
	v_cvt_pk_bf16_f32 v188, v136, v137
	v_cvt_pk_bf16_f32 v189, v138, v139
	global_store_dwordx2 v121, v[188:189], s[12:13] offset:1024
	v_pk_add_f32 v[156:157], v[156:157], 1.0 op_sel_hi:[1,0]
	v_pk_add_f32 v[158:159], v[158:159], 1.0 op_sel_hi:[1,0]
	v_pk_mul_f32 v[156:157], v[112:113], v[156:157]
	v_pk_mul_f32 v[158:159], v[114:115], v[158:159]
	v_pk_mul_f32 v[140:141], v[140:141], v[210:211] op_sel_hi:[1,0]
	v_pk_mul_f32 v[142:143], v[142:143], v[210:211] op_sel_hi:[1,0]
	v_pk_fma_f32 v[140:141], v[156:157], v[140:141], v[172:173]
	v_pk_fma_f32 v[142:143], v[158:159], v[142:143], v[174:175]
	v_cvt_pk_bf16_f32 v190, v140, v141
	v_cvt_pk_bf16_f32 v191, v142, v143
	global_store_dwordx2 v121, v[190:191], s[12:13] offset:1536
	s_add_u32 s10, s10, 0x400000
	s_addc_u32 s11, s11, 0
	s_add_u32 s12, s12, 0x400000
	s_addc_u32 s13, s13, 0
	s_add_u32 s4, s4, 0x800000
	s_addc_u32 s5, s5, 0
	s_add_u32 s6, s6, 0x3000
	s_addc_u32 s7, s7, 0
	s_add_u32 s8, s8, 0x3000
	s_addc_u32 s9, s9, 0
	global_load_dwordx4 v[128:131], v120, s[4:5] nt
	global_load_dwordx4 v[132:135], v120, s[4:5] offset:1024 nt
	global_load_dwordx4 v[136:139], v120, s[4:5] offset:2048 nt
	global_load_dwordx4 v[140:143], v120, s[4:5] offset:3072 nt
	global_load_dwordx4 v[144:147], v120, s[8:9]
	global_load_dwordx4 v[148:151], v120, s[8:9] offset:1024
	global_load_dwordx4 v[152:155], v120, s[8:9] offset:2048
	global_load_dwordx4 v[156:159], v120, s[8:9] offset:3072
	global_load_dwordx4 v[160:163], v120, s[6:7]
	global_load_dwordx4 v[164:167], v120, s[6:7] offset:1024
	global_load_dwordx4 v[168:171], v120, s[6:7] offset:2048
	global_load_dwordx4 v[172:175], v120, s[6:7] offset:3072
	s_waitcnt vmcnt(20)
	v_pk_add_f32 v[0:1], v[0:1], v[84:85]
	v_pk_add_f32 v[2:3], v[2:3], v[86:87]
	v_pk_add_f32 v[4:5], v[4:5], v[88:89]
	v_pk_add_f32 v[6:7], v[6:7], v[90:91]
	v_pk_add_f32 v[8:9], v[8:9], v[92:93]
	v_pk_add_f32 v[10:11], v[10:11], v[94:95]
	v_pk_add_f32 v[12:13], v[12:13], v[96:97]
	v_pk_add_f32 v[14:15], v[14:15], v[98:99]
	v_cvt_pk_bf16_f32 v176, v0, v1
	v_cvt_pk_bf16_f32 v177, v2, v3
	global_store_dwordx2 v121, v[176:177], s[10:11]
	v_cvt_pk_bf16_f32 v178, v4, v5
	v_cvt_pk_bf16_f32 v179, v6, v7
	global_store_dwordx2 v121, v[178:179], s[10:11] offset:512
	v_cvt_pk_bf16_f32 v180, v8, v9
	v_cvt_pk_bf16_f32 v181, v10, v11
	global_store_dwordx2 v121, v[180:181], s[10:11] offset:1024
	v_cvt_pk_bf16_f32 v182, v12, v13
	v_cvt_pk_bf16_f32 v183, v14, v15
	global_store_dwordx2 v121, v[182:183], s[10:11] offset:1536
	v_mul_f32_e32 v192, v1, v1
	v_mul_f32_e32 v193, v3, v3
	v_mul_f32_e32 v194, v5, v5
	v_mul_f32_e32 v195, v7, v7
	v_mul_f32_e32 v196, v9, v9
	v_mul_f32_e32 v197, v11, v11
	v_pk_mul_f32 v[198:199], v[14:15], v[14:15]
	v_pk_mul_f32 v[200:201], v[12:13], v[12:13]
	v_fmac_f32_e32 v192, v0, v0
	v_fmac_f32_e32 v193, v2, v2
	v_fmac_f32_e32 v194, v4, v4
	v_fmac_f32_e32 v195, v6, v6
	v_fmac_f32_e32 v196, v8, v8
	v_fmac_f32_e32 v197, v10, v10
	v_add_f32_e32 v202, v201, v200
	v_add_f32_e32 v203, v198, v199
	v_add_f32_e32 v192, v192, v193
	v_add_f32_e32 v193, v194, v195
	v_add_f32_e32 v194, v196, v197
	v_add_f32_e32 v192, v192, v193
	v_add_f32_e32 v202, v202, v203
	v_add_f32_e32 v193, v192, v194
	v_add_f32_e32 v202, v193, v202
	s_nop 1
	v_add_f32_dpp v202, v202, v202 quad_perm:[1,0,3,2] row_mask:0xf bank_mask:0xf bound_ctrl:1
	s_nop 1
	v_add_f32_dpp v202, v202, v202 quad_perm:[2,3,0,1] row_mask:0xf bank_mask:0xf bound_ctrl:1
	s_nop 1
	v_add_f32_dpp v202, v202, v202 row_half_mirror row_mask:0xf bank_mask:0xf bound_ctrl:1
	s_nop 1
	v_add_f32_dpp v202, v202, v202 row_mirror row_mask:0xf bank_mask:0xf bound_ctrl:1
	s_nop 1
	v_readlane_b32 s14, v202, 16
	v_readlane_b32 s15, v202, 48
	v_readlane_b32 s18, v202, 0
	v_readlane_b32 s19, v202, 32
	s_nop 1
	v_mov_b32_e32 v202, s14
	v_mov_b32_e32 v203, s15
	v_pk_add_f32 v[202:203], s[18:19], v[202:203]
	s_nop 0
	v_add_f32_e32 v202, v202, v203
	v_fmamk_f32 v202, v202, 0x3a800000, v116
	v_mul_f32_e32 v203, 0x4f800000, v202
	v_cmp_gt_f32_e32 vcc, s3, v202
	s_nop 1
	v_cndmask_b32_e32 v202, v202, v203, vcc
	v_sqrt_f32_e32 v203, v202
	s_nop 0
	v_add_u32_e32 v204, -1, v203
	v_add_u32_e32 v205, 1, v203
	v_fma_f32 v206, -v204, v203, v202
	v_fma_f32 v207, -v205, v203, v202
	v_cmp_ge_f32_e64 s[20:21], 0, v206
	s_nop 1
	v_cndmask_b32_e64 v203, v203, v204, s[20:21]
	v_cmp_lt_f32_e64 s[20:21], 0, v207
	s_nop 1
	v_cndmask_b32_e64 v203, v203, v205, s[20:21]
	v_mul_f32_e32 v204, 0x37800000, v203
	v_cndmask_b32_e32 v203, v203, v204, vcc
	v_cmp_class_f32_e32 vcc, v202, v117
	s_nop 1
	v_cndmask_b32_e32 v204, v203, v202, vcc
	v_div_scale_f32 v205, s[20:21], v204, v204, 1.0
	v_rcp_f32_e32 v206, v205
	v_div_scale_f32 v207, vcc, 1.0, v204, 1.0
	s_nop 0
	v_fma_f32 v208, -v205, v206, 1.0
	v_fmac_f32_e32 v206, v208, v206
	v_mul_f32_e32 v208, v207, v206
	v_fma_f32 v209, -v205, v208, v207
	v_fmac_f32_e32 v208, v209, v206
	v_fma_f32 v205, -v205, v208, v207
	v_div_fmas_f32 v205, v205, v206, v208
	v_div_fixup_f32 v210, v205, v204, 1.0
	v_pk_add_f32 v[16:17], v[16:17], 1.0 op_sel_hi:[1,0]
	v_pk_add_f32 v[18:19], v[18:19], 1.0 op_sel_hi:[1,0]
	v_pk_mul_f32 v[16:17], v[100:101], v[16:17]
	v_pk_mul_f32 v[18:19], v[102:103], v[18:19]
	v_pk_mul_f32 v[0:1], v[0:1], v[210:211] op_sel_hi:[1,0]
	v_pk_mul_f32 v[2:3], v[2:3], v[210:211] op_sel_hi:[1,0]
	v_pk_fma_f32 v[0:1], v[16:17], v[0:1], v[32:33]
	v_pk_fma_f32 v[2:3], v[18:19], v[2:3], v[34:35]
	v_cvt_pk_bf16_f32 v184, v0, v1
	v_cvt_pk_bf16_f32 v185, v2, v3
	global_store_dwordx2 v121, v[184:185], s[12:13]
	v_pk_add_f32 v[20:21], v[20:21], 1.0 op_sel_hi:[1,0]
	v_pk_add_f32 v[22:23], v[22:23], 1.0 op_sel_hi:[1,0]
	v_pk_mul_f32 v[20:21], v[104:105], v[20:21]
	v_pk_mul_f32 v[22:23], v[106:107], v[22:23]
	v_pk_mul_f32 v[4:5], v[4:5], v[210:211] op_sel_hi:[1,0]
	v_pk_mul_f32 v[6:7], v[6:7], v[210:211] op_sel_hi:[1,0]
	v_pk_fma_f32 v[4:5], v[20:21], v[4:5], v[36:37]
	v_pk_fma_f32 v[6:7], v[22:23], v[6:7], v[38:39]
	v_cvt_pk_bf16_f32 v186, v4, v5
	v_cvt_pk_bf16_f32 v187, v6, v7
	global_store_dwordx2 v121, v[186:187], s[12:13] offset:512
	v_pk_add_f32 v[24:25], v[24:25], 1.0 op_sel_hi:[1,0]
	v_pk_add_f32 v[26:27], v[26:27], 1.0 op_sel_hi:[1,0]
	v_pk_mul_f32 v[24:25], v[108:109], v[24:25]
	v_pk_mul_f32 v[26:27], v[110:111], v[26:27]
	v_pk_mul_f32 v[8:9], v[8:9], v[210:211] op_sel_hi:[1,0]
	v_pk_mul_f32 v[10:11], v[10:11], v[210:211] op_sel_hi:[1,0]
	v_pk_fma_f32 v[8:9], v[24:25], v[8:9], v[40:41]
	v_pk_fma_f32 v[10:11], v[26:27], v[10:11], v[42:43]
	v_cvt_pk_bf16_f32 v188, v8, v9
	v_cvt_pk_bf16_f32 v189, v10, v11
	global_store_dwordx2 v121, v[188:189], s[12:13] offset:1024
	v_pk_add_f32 v[28:29], v[28:29], 1.0 op_sel_hi:[1,0]
	v_pk_add_f32 v[30:31], v[30:31], 1.0 op_sel_hi:[1,0]
	v_pk_mul_f32 v[28:29], v[112:113], v[28:29]
	v_pk_mul_f32 v[30:31], v[114:115], v[30:31]
	v_pk_mul_f32 v[12:13], v[12:13], v[210:211] op_sel_hi:[1,0]
	v_pk_mul_f32 v[14:15], v[14:15], v[210:211] op_sel_hi:[1,0]
	v_pk_fma_f32 v[12:13], v[28:29], v[12:13], v[44:45]
	v_pk_fma_f32 v[14:15], v[30:31], v[14:15], v[46:47]
	v_cvt_pk_bf16_f32 v190, v12, v13
	v_cvt_pk_bf16_f32 v191, v14, v15
	global_store_dwordx2 v121, v[190:191], s[12:13] offset:1536
	s_add_u32 s10, s10, 0x400000
	s_addc_u32 s11, s11, 0
	s_add_u32 s12, s12, 0x400000
	s_addc_u32 s13, s13, 0
	s_add_u32 s4, s4, 0x800000
	s_addc_u32 s5, s5, 0
	s_add_u32 s6, s6, 0x3000
	s_addc_u32 s7, s7, 0
	s_add_u32 s8, s8, 0x3000
	s_addc_u32 s9, s9, 0
	global_load_dwordx4 v[0:3], v120, s[4:5] nt
	global_load_dwordx4 v[4:7], v120, s[4:5] offset:1024 nt
	global_load_dwordx4 v[8:11], v120, s[4:5] offset:2048 nt
	global_load_dwordx4 v[12:15], v120, s[4:5] offset:3072 nt
	global_load_dwordx4 v[16:19], v120, s[8:9]
	global_load_dwordx4 v[20:23], v120, s[8:9] offset:1024
	global_load_dwordx4 v[24:27], v120, s[8:9] offset:2048
	global_load_dwordx4 v[28:31], v120, s[8:9] offset:3072
	global_load_dwordx4 v[32:35], v120, s[6:7]
	global_load_dwordx4 v[36:39], v120, s[6:7] offset:1024
	global_load_dwordx4 v[40:43], v120, s[6:7] offset:2048
	global_load_dwordx4 v[44:47], v120, s[6:7] offset:3072
	s_waitcnt vmcnt(20)
	v_pk_add_f32 v[128:129], v[128:129], v[84:85]
	v_pk_add_f32 v[130:131], v[130:131], v[86:87]
	v_pk_add_f32 v[132:133], v[132:133], v[88:89]
	v_pk_add_f32 v[134:135], v[134:135], v[90:91]
	v_pk_add_f32 v[136:137], v[136:137], v[92:93]
	v_pk_add_f32 v[138:139], v[138:139], v[94:95]
	v_pk_add_f32 v[140:141], v[140:141], v[96:97]
	v_pk_add_f32 v[142:143], v[142:143], v[98:99]
	v_cvt_pk_bf16_f32 v176, v128, v129
	v_cvt_pk_bf16_f32 v177, v130, v131
	global_store_dwordx2 v121, v[176:177], s[10:11]
	v_cvt_pk_bf16_f32 v178, v132, v133
	v_cvt_pk_bf16_f32 v179, v134, v135
	global_store_dwordx2 v121, v[178:179], s[10:11] offset:512
	v_cvt_pk_bf16_f32 v180, v136, v137
	v_cvt_pk_bf16_f32 v181, v138, v139
	global_store_dwordx2 v121, v[180:181], s[10:11] offset:1024
	v_cvt_pk_bf16_f32 v182, v140, v141
	v_cvt_pk_bf16_f32 v183, v142, v143
	global_store_dwordx2 v121, v[182:183], s[10:11] offset:1536
	v_mul_f32_e32 v192, v129, v129
	v_mul_f32_e32 v193, v131, v131
	v_mul_f32_e32 v194, v133, v133
	v_mul_f32_e32 v195, v135, v135
	v_mul_f32_e32 v196, v137, v137
	v_mul_f32_e32 v197, v139, v139
	v_pk_mul_f32 v[198:199], v[142:143], v[142:143]
	v_pk_mul_f32 v[200:201], v[140:141], v[140:141]
	v_fmac_f32_e32 v192, v128, v128
	v_fmac_f32_e32 v193, v130, v130
	v_fmac_f32_e32 v194, v132, v132
	v_fmac_f32_e32 v195, v134, v134
	v_fmac_f32_e32 v196, v136, v136
	v_fmac_f32_e32 v197, v138, v138
	v_add_f32_e32 v202, v201, v200
	v_add_f32_e32 v203, v198, v199
	v_add_f32_e32 v192, v192, v193
	v_add_f32_e32 v193, v194, v195
	v_add_f32_e32 v194, v196, v197
	v_add_f32_e32 v192, v192, v193
	v_add_f32_e32 v202, v202, v203
	v_add_f32_e32 v193, v192, v194
	v_add_f32_e32 v202, v193, v202
	s_nop 1
	v_add_f32_dpp v202, v202, v202 quad_perm:[1,0,3,2] row_mask:0xf bank_mask:0xf bound_ctrl:1
	s_nop 1
	v_add_f32_dpp v202, v202, v202 quad_perm:[2,3,0,1] row_mask:0xf bank_mask:0xf bound_ctrl:1
	s_nop 1
	v_add_f32_dpp v202, v202, v202 row_half_mirror row_mask:0xf bank_mask:0xf bound_ctrl:1
	s_nop 1
	v_add_f32_dpp v202, v202, v202 row_mirror row_mask:0xf bank_mask:0xf bound_ctrl:1
	s_nop 1
	v_readlane_b32 s14, v202, 16
	v_readlane_b32 s15, v202, 48
	v_readlane_b32 s18, v202, 0
	v_readlane_b32 s19, v202, 32
	s_nop 1
	v_mov_b32_e32 v202, s14
	v_mov_b32_e32 v203, s15
	v_pk_add_f32 v[202:203], s[18:19], v[202:203]
	s_nop 0
	v_add_f32_e32 v202, v202, v203
	v_fmamk_f32 v202, v202, 0x3a800000, v116
	v_mul_f32_e32 v203, 0x4f800000, v202
	v_cmp_gt_f32_e32 vcc, s3, v202
	s_nop 1
	v_cndmask_b32_e32 v202, v202, v203, vcc
	v_sqrt_f32_e32 v203, v202
	s_nop 0
	v_add_u32_e32 v204, -1, v203
	v_add_u32_e32 v205, 1, v203
	v_fma_f32 v206, -v204, v203, v202
	v_fma_f32 v207, -v205, v203, v202
	v_cmp_ge_f32_e64 s[20:21], 0, v206
	s_nop 1
	v_cndmask_b32_e64 v203, v203, v204, s[20:21]
	v_cmp_lt_f32_e64 s[20:21], 0, v207
	s_nop 1
	v_cndmask_b32_e64 v203, v203, v205, s[20:21]
	v_mul_f32_e32 v204, 0x37800000, v203
	v_cndmask_b32_e32 v203, v203, v204, vcc
	v_cmp_class_f32_e32 vcc, v202, v117
	s_nop 1
	v_cndmask_b32_e32 v204, v203, v202, vcc
	v_div_scale_f32 v205, s[20:21], v204, v204, 1.0
	v_rcp_f32_e32 v206, v205
	v_div_scale_f32 v207, vcc, 1.0, v204, 1.0
	s_nop 0
	v_fma_f32 v208, -v205, v206, 1.0
	v_fmac_f32_e32 v206, v208, v206
	v_mul_f32_e32 v208, v207, v206
	v_fma_f32 v209, -v205, v208, v207
	v_fmac_f32_e32 v208, v209, v206
	v_fma_f32 v205, -v205, v208, v207
	v_div_fmas_f32 v205, v205, v206, v208
	v_div_fixup_f32 v210, v205, v204, 1.0
	v_pk_add_f32 v[144:145], v[144:145], 1.0 op_sel_hi:[1,0]
	v_pk_add_f32 v[146:147], v[146:147], 1.0 op_sel_hi:[1,0]
	v_pk_mul_f32 v[144:145], v[100:101], v[144:145]
	v_pk_mul_f32 v[146:147], v[102:103], v[146:147]
	v_pk_mul_f32 v[128:129], v[128:129], v[210:211] op_sel_hi:[1,0]
	v_pk_mul_f32 v[130:131], v[130:131], v[210:211] op_sel_hi:[1,0]
	v_pk_fma_f32 v[128:129], v[144:145], v[128:129], v[160:161]
	v_pk_fma_f32 v[130:131], v[146:147], v[130:131], v[162:163]
	v_cvt_pk_bf16_f32 v184, v128, v129
	v_cvt_pk_bf16_f32 v185, v130, v131
	global_store_dwordx2 v121, v[184:185], s[12:13]
	v_pk_add_f32 v[148:149], v[148:149], 1.0 op_sel_hi:[1,0]
	v_pk_add_f32 v[150:151], v[150:151], 1.0 op_sel_hi:[1,0]
	v_pk_mul_f32 v[148:149], v[104:105], v[148:149]
	v_pk_mul_f32 v[150:151], v[106:107], v[150:151]
	v_pk_mul_f32 v[132:133], v[132:133], v[210:211] op_sel_hi:[1,0]
	v_pk_mul_f32 v[134:135], v[134:135], v[210:211] op_sel_hi:[1,0]
	v_pk_fma_f32 v[132:133], v[148:149], v[132:133], v[164:165]
	v_pk_fma_f32 v[134:135], v[150:151], v[134:135], v[166:167]
	v_cvt_pk_bf16_f32 v186, v132, v133
	v_cvt_pk_bf16_f32 v187, v134, v135
	global_store_dwordx2 v121, v[186:187], s[12:13] offset:512
	v_pk_add_f32 v[152:153], v[152:153], 1.0 op_sel_hi:[1,0]
	v_pk_add_f32 v[154:155], v[154:155], 1.0 op_sel_hi:[1,0]
	v_pk_mul_f32 v[152:153], v[108:109], v[152:153]
	v_pk_mul_f32 v[154:155], v[110:111], v[154:155]
	v_pk_mul_f32 v[136:137], v[136:137], v[210:211] op_sel_hi:[1,0]
	v_pk_mul_f32 v[138:139], v[138:139], v[210:211] op_sel_hi:[1,0]
	v_pk_fma_f32 v[136:137], v[152:153], v[136:137], v[168:169]
	v_pk_fma_f32 v[138:139], v[154:155], v[138:139], v[170:171]
	v_cvt_pk_bf16_f32 v188, v136, v137
	v_cvt_pk_bf16_f32 v189, v138, v139
	global_store_dwordx2 v121, v[188:189], s[12:13] offset:1024
	v_pk_add_f32 v[156:157], v[156:157], 1.0 op_sel_hi:[1,0]
	v_pk_add_f32 v[158:159], v[158:159], 1.0 op_sel_hi:[1,0]
	v_pk_mul_f32 v[156:157], v[112:113], v[156:157]
	v_pk_mul_f32 v[158:159], v[114:115], v[158:159]
	v_pk_mul_f32 v[140:141], v[140:141], v[210:211] op_sel_hi:[1,0]
	v_pk_mul_f32 v[142:143], v[142:143], v[210:211] op_sel_hi:[1,0]
	v_pk_fma_f32 v[140:141], v[156:157], v[140:141], v[172:173]
	v_pk_fma_f32 v[142:143], v[158:159], v[142:143], v[174:175]
	v_cvt_pk_bf16_f32 v190, v140, v141
	v_cvt_pk_bf16_f32 v191, v142, v143
	global_store_dwordx2 v121, v[190:191], s[12:13] offset:1536
	s_add_u32 s10, s10, 0x400000
	s_addc_u32 s11, s11, 0
	s_add_u32 s12, s12, 0x400000
	s_addc_u32 s13, s13, 0
	s_add_u32 s4, s4, 0x800000
	s_addc_u32 s5, s5, 0
	s_add_u32 s6, s6, 0x3000
	s_addc_u32 s7, s7, 0
	s_add_u32 s8, s8, 0x3000
	s_addc_u32 s9, s9, 0
	global_load_dwordx4 v[128:131], v120, s[4:5] nt
	global_load_dwordx4 v[132:135], v120, s[4:5] offset:1024 nt
	global_load_dwordx4 v[136:139], v120, s[4:5] offset:2048 nt
	global_load_dwordx4 v[140:143], v120, s[4:5] offset:3072 nt
	global_load_dwordx4 v[144:147], v120, s[8:9]
	global_load_dwordx4 v[148:151], v120, s[8:9] offset:1024
	global_load_dwordx4 v[152:155], v120, s[8:9] offset:2048
	global_load_dwordx4 v[156:159], v120, s[8:9] offset:3072
	global_load_dwordx4 v[160:163], v120, s[6:7]
	global_load_dwordx4 v[164:167], v120, s[6:7] offset:1024
	global_load_dwordx4 v[168:171], v120, s[6:7] offset:2048
	global_load_dwordx4 v[172:175], v120, s[6:7] offset:3072
	s_waitcnt vmcnt(20)
	v_pk_add_f32 v[0:1], v[0:1], v[84:85]
	v_pk_add_f32 v[2:3], v[2:3], v[86:87]
	v_pk_add_f32 v[4:5], v[4:5], v[88:89]
	v_pk_add_f32 v[6:7], v[6:7], v[90:91]
	v_pk_add_f32 v[8:9], v[8:9], v[92:93]
	v_pk_add_f32 v[10:11], v[10:11], v[94:95]
	v_pk_add_f32 v[12:13], v[12:13], v[96:97]
	v_pk_add_f32 v[14:15], v[14:15], v[98:99]
	v_cvt_pk_bf16_f32 v176, v0, v1
	v_cvt_pk_bf16_f32 v177, v2, v3
	global_store_dwordx2 v121, v[176:177], s[10:11]
	v_cvt_pk_bf16_f32 v178, v4, v5
	v_cvt_pk_bf16_f32 v179, v6, v7
	global_store_dwordx2 v121, v[178:179], s[10:11] offset:512
	v_cvt_pk_bf16_f32 v180, v8, v9
	v_cvt_pk_bf16_f32 v181, v10, v11
	global_store_dwordx2 v121, v[180:181], s[10:11] offset:1024
	v_cvt_pk_bf16_f32 v182, v12, v13
	v_cvt_pk_bf16_f32 v183, v14, v15
	global_store_dwordx2 v121, v[182:183], s[10:11] offset:1536
	v_mul_f32_e32 v192, v1, v1
	v_mul_f32_e32 v193, v3, v3
	v_mul_f32_e32 v194, v5, v5
	v_mul_f32_e32 v195, v7, v7
	v_mul_f32_e32 v196, v9, v9
	v_mul_f32_e32 v197, v11, v11
	v_pk_mul_f32 v[198:199], v[14:15], v[14:15]
	v_pk_mul_f32 v[200:201], v[12:13], v[12:13]
	v_fmac_f32_e32 v192, v0, v0
	v_fmac_f32_e32 v193, v2, v2
	v_fmac_f32_e32 v194, v4, v4
	v_fmac_f32_e32 v195, v6, v6
	v_fmac_f32_e32 v196, v8, v8
	v_fmac_f32_e32 v197, v10, v10
	v_add_f32_e32 v202, v201, v200
	v_add_f32_e32 v203, v198, v199
	v_add_f32_e32 v192, v192, v193
	v_add_f32_e32 v193, v194, v195
	v_add_f32_e32 v194, v196, v197
	v_add_f32_e32 v192, v192, v193
	v_add_f32_e32 v202, v202, v203
	v_add_f32_e32 v193, v192, v194
	v_add_f32_e32 v202, v193, v202
	s_nop 1
	v_add_f32_dpp v202, v202, v202 quad_perm:[1,0,3,2] row_mask:0xf bank_mask:0xf bound_ctrl:1
	s_nop 1
	v_add_f32_dpp v202, v202, v202 quad_perm:[2,3,0,1] row_mask:0xf bank_mask:0xf bound_ctrl:1
	s_nop 1
	v_add_f32_dpp v202, v202, v202 row_half_mirror row_mask:0xf bank_mask:0xf bound_ctrl:1
	s_nop 1
	v_add_f32_dpp v202, v202, v202 row_mirror row_mask:0xf bank_mask:0xf bound_ctrl:1
	s_nop 1
	v_readlane_b32 s14, v202, 16
	v_readlane_b32 s15, v202, 48
	v_readlane_b32 s18, v202, 0
	v_readlane_b32 s19, v202, 32
	s_nop 1
	v_mov_b32_e32 v202, s14
	v_mov_b32_e32 v203, s15
	v_pk_add_f32 v[202:203], s[18:19], v[202:203]
	s_nop 0
	v_add_f32_e32 v202, v202, v203
	v_fmamk_f32 v202, v202, 0x3a800000, v116
	v_mul_f32_e32 v203, 0x4f800000, v202
	v_cmp_gt_f32_e32 vcc, s3, v202
	s_nop 1
	v_cndmask_b32_e32 v202, v202, v203, vcc
	v_sqrt_f32_e32 v203, v202
	s_nop 0
	v_add_u32_e32 v204, -1, v203
	v_add_u32_e32 v205, 1, v203
	v_fma_f32 v206, -v204, v203, v202
	v_fma_f32 v207, -v205, v203, v202
	v_cmp_ge_f32_e64 s[20:21], 0, v206
	s_nop 1
	v_cndmask_b32_e64 v203, v203, v204, s[20:21]
	v_cmp_lt_f32_e64 s[20:21], 0, v207
	s_nop 1
	v_cndmask_b32_e64 v203, v203, v205, s[20:21]
	v_mul_f32_e32 v204, 0x37800000, v203
	v_cndmask_b32_e32 v203, v203, v204, vcc
	v_cmp_class_f32_e32 vcc, v202, v117
	s_nop 1
	v_cndmask_b32_e32 v204, v203, v202, vcc
	v_div_scale_f32 v205, s[20:21], v204, v204, 1.0
	v_rcp_f32_e32 v206, v205
	v_div_scale_f32 v207, vcc, 1.0, v204, 1.0
	s_nop 0
	v_fma_f32 v208, -v205, v206, 1.0
	v_fmac_f32_e32 v206, v208, v206
	v_mul_f32_e32 v208, v207, v206
	v_fma_f32 v209, -v205, v208, v207
	v_fmac_f32_e32 v208, v209, v206
	v_fma_f32 v205, -v205, v208, v207
	v_div_fmas_f32 v205, v205, v206, v208
	v_div_fixup_f32 v210, v205, v204, 1.0
	v_pk_add_f32 v[16:17], v[16:17], 1.0 op_sel_hi:[1,0]
	v_pk_add_f32 v[18:19], v[18:19], 1.0 op_sel_hi:[1,0]
	v_pk_mul_f32 v[16:17], v[100:101], v[16:17]
	v_pk_mul_f32 v[18:19], v[102:103], v[18:19]
	v_pk_mul_f32 v[0:1], v[0:1], v[210:211] op_sel_hi:[1,0]
	v_pk_mul_f32 v[2:3], v[2:3], v[210:211] op_sel_hi:[1,0]
	v_pk_fma_f32 v[0:1], v[16:17], v[0:1], v[32:33]
	v_pk_fma_f32 v[2:3], v[18:19], v[2:3], v[34:35]
	v_cvt_pk_bf16_f32 v184, v0, v1
	v_cvt_pk_bf16_f32 v185, v2, v3
	global_store_dwordx2 v121, v[184:185], s[12:13]
	v_pk_add_f32 v[20:21], v[20:21], 1.0 op_sel_hi:[1,0]
	v_pk_add_f32 v[22:23], v[22:23], 1.0 op_sel_hi:[1,0]
	v_pk_mul_f32 v[20:21], v[104:105], v[20:21]
	v_pk_mul_f32 v[22:23], v[106:107], v[22:23]
	v_pk_mul_f32 v[4:5], v[4:5], v[210:211] op_sel_hi:[1,0]
	v_pk_mul_f32 v[6:7], v[6:7], v[210:211] op_sel_hi:[1,0]
	v_pk_fma_f32 v[4:5], v[20:21], v[4:5], v[36:37]
	v_pk_fma_f32 v[6:7], v[22:23], v[6:7], v[38:39]
	v_cvt_pk_bf16_f32 v186, v4, v5
	v_cvt_pk_bf16_f32 v187, v6, v7
	global_store_dwordx2 v121, v[186:187], s[12:13] offset:512
	v_pk_add_f32 v[24:25], v[24:25], 1.0 op_sel_hi:[1,0]
	v_pk_add_f32 v[26:27], v[26:27], 1.0 op_sel_hi:[1,0]
	v_pk_mul_f32 v[24:25], v[108:109], v[24:25]
	v_pk_mul_f32 v[26:27], v[110:111], v[26:27]
	v_pk_mul_f32 v[8:9], v[8:9], v[210:211] op_sel_hi:[1,0]
	v_pk_mul_f32 v[10:11], v[10:11], v[210:211] op_sel_hi:[1,0]
	v_pk_fma_f32 v[8:9], v[24:25], v[8:9], v[40:41]
	v_pk_fma_f32 v[10:11], v[26:27], v[10:11], v[42:43]
	v_cvt_pk_bf16_f32 v188, v8, v9
	v_cvt_pk_bf16_f32 v189, v10, v11
	global_store_dwordx2 v121, v[188:189], s[12:13] offset:1024
	v_pk_add_f32 v[28:29], v[28:29], 1.0 op_sel_hi:[1,0]
	v_pk_add_f32 v[30:31], v[30:31], 1.0 op_sel_hi:[1,0]
	v_pk_mul_f32 v[28:29], v[112:113], v[28:29]
	v_pk_mul_f32 v[30:31], v[114:115], v[30:31]
	v_pk_mul_f32 v[12:13], v[12:13], v[210:211] op_sel_hi:[1,0]
	v_pk_mul_f32 v[14:15], v[14:15], v[210:211] op_sel_hi:[1,0]
	v_pk_fma_f32 v[12:13], v[28:29], v[12:13], v[44:45]
	v_pk_fma_f32 v[14:15], v[30:31], v[14:15], v[46:47]
	v_cvt_pk_bf16_f32 v190, v12, v13
	v_cvt_pk_bf16_f32 v191, v14, v15
	global_store_dwordx2 v121, v[190:191], s[12:13] offset:1536
	s_add_u32 s10, s10, 0x400000
	s_addc_u32 s11, s11, 0
	s_add_u32 s12, s12, 0x400000
	s_addc_u32 s13, s13, 0
	s_mov_b64 s[4:5], s[22:23]
	s_add_u32 s6, s6, 0x3000
	s_addc_u32 s7, s7, 0
	s_add_u32 s8, s8, 0x3000
	s_addc_u32 s9, s9, 0
	global_load_dwordx4 v[0:3], v120, s[4:5] nt
	global_load_dwordx4 v[4:7], v120, s[4:5] offset:1024 nt
	global_load_dwordx4 v[8:11], v120, s[4:5] offset:2048 nt
	global_load_dwordx4 v[12:15], v120, s[4:5] offset:3072 nt
	global_load_dwordx4 v[16:19], v120, s[8:9]
	global_load_dwordx4 v[20:23], v120, s[8:9] offset:1024
	global_load_dwordx4 v[24:27], v120, s[8:9] offset:2048
	global_load_dwordx4 v[28:31], v120, s[8:9] offset:3072
	global_load_dwordx4 v[32:35], v120, s[6:7]
	global_load_dwordx4 v[36:39], v120, s[6:7] offset:1024
	global_load_dwordx4 v[40:43], v120, s[6:7] offset:2048
	global_load_dwordx4 v[44:47], v120, s[6:7] offset:3072
	s_waitcnt vmcnt(20)
	v_pk_add_f32 v[128:129], v[128:129], v[84:85]
	v_pk_add_f32 v[130:131], v[130:131], v[86:87]
	v_pk_add_f32 v[132:133], v[132:133], v[88:89]
	v_pk_add_f32 v[134:135], v[134:135], v[90:91]
	v_pk_add_f32 v[136:137], v[136:137], v[92:93]
	v_pk_add_f32 v[138:139], v[138:139], v[94:95]
	v_pk_add_f32 v[140:141], v[140:141], v[96:97]
	v_pk_add_f32 v[142:143], v[142:143], v[98:99]
	v_cvt_pk_bf16_f32 v176, v128, v129
	v_cvt_pk_bf16_f32 v177, v130, v131
	global_store_dwordx2 v121, v[176:177], s[10:11]
	v_cvt_pk_bf16_f32 v178, v132, v133
	v_cvt_pk_bf16_f32 v179, v134, v135
	global_store_dwordx2 v121, v[178:179], s[10:11] offset:512
	v_cvt_pk_bf16_f32 v180, v136, v137
	v_cvt_pk_bf16_f32 v181, v138, v139
	global_store_dwordx2 v121, v[180:181], s[10:11] offset:1024
	v_cvt_pk_bf16_f32 v182, v140, v141
	v_cvt_pk_bf16_f32 v183, v142, v143
	global_store_dwordx2 v121, v[182:183], s[10:11] offset:1536
	v_mul_f32_e32 v192, v129, v129
	v_mul_f32_e32 v193, v131, v131
	v_mul_f32_e32 v194, v133, v133
	v_mul_f32_e32 v195, v135, v135
	v_mul_f32_e32 v196, v137, v137
	v_mul_f32_e32 v197, v139, v139
	v_pk_mul_f32 v[198:199], v[142:143], v[142:143]
	v_pk_mul_f32 v[200:201], v[140:141], v[140:141]
	v_fmac_f32_e32 v192, v128, v128
	v_fmac_f32_e32 v193, v130, v130
	v_fmac_f32_e32 v194, v132, v132
	v_fmac_f32_e32 v195, v134, v134
	v_fmac_f32_e32 v196, v136, v136
	v_fmac_f32_e32 v197, v138, v138
	v_add_f32_e32 v202, v201, v200
	v_add_f32_e32 v203, v198, v199
	v_add_f32_e32 v192, v192, v193
	v_add_f32_e32 v193, v194, v195
	v_add_f32_e32 v194, v196, v197
	v_add_f32_e32 v192, v192, v193
	v_add_f32_e32 v202, v202, v203
	v_add_f32_e32 v193, v192, v194
	v_add_f32_e32 v202, v193, v202
	s_nop 1
	v_add_f32_dpp v202, v202, v202 quad_perm:[1,0,3,2] row_mask:0xf bank_mask:0xf bound_ctrl:1
	s_nop 1
	v_add_f32_dpp v202, v202, v202 quad_perm:[2,3,0,1] row_mask:0xf bank_mask:0xf bound_ctrl:1
	s_nop 1
	v_add_f32_dpp v202, v202, v202 row_half_mirror row_mask:0xf bank_mask:0xf bound_ctrl:1
	s_nop 1
	v_add_f32_dpp v202, v202, v202 row_mirror row_mask:0xf bank_mask:0xf bound_ctrl:1
	s_nop 1
	v_readlane_b32 s14, v202, 16
	v_readlane_b32 s15, v202, 48
	v_readlane_b32 s18, v202, 0
	v_readlane_b32 s19, v202, 32
	s_nop 1
	v_mov_b32_e32 v202, s14
	v_mov_b32_e32 v203, s15
	v_pk_add_f32 v[202:203], s[18:19], v[202:203]
	s_nop 0
	v_add_f32_e32 v202, v202, v203
	v_fmamk_f32 v202, v202, 0x3a800000, v116
	v_mul_f32_e32 v203, 0x4f800000, v202
	v_cmp_gt_f32_e32 vcc, s3, v202
	s_nop 1
	v_cndmask_b32_e32 v202, v202, v203, vcc
	v_sqrt_f32_e32 v203, v202
	s_nop 0
	v_add_u32_e32 v204, -1, v203
	v_add_u32_e32 v205, 1, v203
	v_fma_f32 v206, -v204, v203, v202
	v_fma_f32 v207, -v205, v203, v202
	v_cmp_ge_f32_e64 s[20:21], 0, v206
	s_nop 1
	v_cndmask_b32_e64 v203, v203, v204, s[20:21]
	v_cmp_lt_f32_e64 s[20:21], 0, v207
	s_nop 1
	v_cndmask_b32_e64 v203, v203, v205, s[20:21]
	v_mul_f32_e32 v204, 0x37800000, v203
	v_cndmask_b32_e32 v203, v203, v204, vcc
	v_cmp_class_f32_e32 vcc, v202, v117
	s_nop 1
	v_cndmask_b32_e32 v204, v203, v202, vcc
	v_div_scale_f32 v205, s[20:21], v204, v204, 1.0
	v_rcp_f32_e32 v206, v205
	v_div_scale_f32 v207, vcc, 1.0, v204, 1.0
	s_nop 0
	v_fma_f32 v208, -v205, v206, 1.0
	v_fmac_f32_e32 v206, v208, v206
	v_mul_f32_e32 v208, v207, v206
	v_fma_f32 v209, -v205, v208, v207
	v_fmac_f32_e32 v208, v209, v206
	v_fma_f32 v205, -v205, v208, v207
	v_div_fmas_f32 v205, v205, v206, v208
	v_div_fixup_f32 v210, v205, v204, 1.0
	v_pk_add_f32 v[144:145], v[144:145], 1.0 op_sel_hi:[1,0]
	v_pk_add_f32 v[146:147], v[146:147], 1.0 op_sel_hi:[1,0]
	v_pk_mul_f32 v[144:145], v[100:101], v[144:145]
	v_pk_mul_f32 v[146:147], v[102:103], v[146:147]
	v_pk_mul_f32 v[128:129], v[128:129], v[210:211] op_sel_hi:[1,0]
	v_pk_mul_f32 v[130:131], v[130:131], v[210:211] op_sel_hi:[1,0]
	v_pk_fma_f32 v[128:129], v[144:145], v[128:129], v[160:161]
	v_pk_fma_f32 v[130:131], v[146:147], v[130:131], v[162:163]
	v_cvt_pk_bf16_f32 v184, v128, v129
	v_cvt_pk_bf16_f32 v185, v130, v131
	global_store_dwordx2 v121, v[184:185], s[12:13]
	v_pk_add_f32 v[148:149], v[148:149], 1.0 op_sel_hi:[1,0]
	v_pk_add_f32 v[150:151], v[150:151], 1.0 op_sel_hi:[1,0]
	v_pk_mul_f32 v[148:149], v[104:105], v[148:149]
	v_pk_mul_f32 v[150:151], v[106:107], v[150:151]
	v_pk_mul_f32 v[132:133], v[132:133], v[210:211] op_sel_hi:[1,0]
	v_pk_mul_f32 v[134:135], v[134:135], v[210:211] op_sel_hi:[1,0]
	v_pk_fma_f32 v[132:133], v[148:149], v[132:133], v[164:165]
	v_pk_fma_f32 v[134:135], v[150:151], v[134:135], v[166:167]
	v_cvt_pk_bf16_f32 v186, v132, v133
	v_cvt_pk_bf16_f32 v187, v134, v135
	global_store_dwordx2 v121, v[186:187], s[12:13] offset:512
	v_pk_add_f32 v[152:153], v[152:153], 1.0 op_sel_hi:[1,0]
	v_pk_add_f32 v[154:155], v[154:155], 1.0 op_sel_hi:[1,0]
	v_pk_mul_f32 v[152:153], v[108:109], v[152:153]
	v_pk_mul_f32 v[154:155], v[110:111], v[154:155]
	v_pk_mul_f32 v[136:137], v[136:137], v[210:211] op_sel_hi:[1,0]
	v_pk_mul_f32 v[138:139], v[138:139], v[210:211] op_sel_hi:[1,0]
	v_pk_fma_f32 v[136:137], v[152:153], v[136:137], v[168:169]
	v_pk_fma_f32 v[138:139], v[154:155], v[138:139], v[170:171]
	v_cvt_pk_bf16_f32 v188, v136, v137
	v_cvt_pk_bf16_f32 v189, v138, v139
	global_store_dwordx2 v121, v[188:189], s[12:13] offset:1024
	v_pk_add_f32 v[156:157], v[156:157], 1.0 op_sel_hi:[1,0]
	v_pk_add_f32 v[158:159], v[158:159], 1.0 op_sel_hi:[1,0]
	v_pk_mul_f32 v[156:157], v[112:113], v[156:157]
	v_pk_mul_f32 v[158:159], v[114:115], v[158:159]
	v_pk_mul_f32 v[140:141], v[140:141], v[210:211] op_sel_hi:[1,0]
	v_pk_mul_f32 v[142:143], v[142:143], v[210:211] op_sel_hi:[1,0]
	v_pk_fma_f32 v[140:141], v[156:157], v[140:141], v[172:173]
	v_pk_fma_f32 v[142:143], v[158:159], v[142:143], v[174:175]
	v_cvt_pk_bf16_f32 v190, v140, v141
	v_cvt_pk_bf16_f32 v191, v142, v143
	global_store_dwordx2 v121, v[190:191], s[12:13] offset:1536
	s_add_u32 s10, s10, 0x400000
	s_addc_u32 s11, s11, 0
	s_add_u32 s12, s12, 0x400000
	s_addc_u32 s13, s13, 0
	s_waitcnt vmcnt(8)
	v_cvt_pk_bf16_f32 v176, v0, v1
	v_cvt_pk_bf16_f32 v177, v2, v3
	global_store_dwordx2 v121, v[176:177], s[10:11]
	v_cvt_pk_bf16_f32 v178, v4, v5
	v_cvt_pk_bf16_f32 v179, v6, v7
	global_store_dwordx2 v121, v[178:179], s[10:11] offset:512
	v_cvt_pk_bf16_f32 v180, v8, v9
	v_cvt_pk_bf16_f32 v181, v10, v11
	global_store_dwordx2 v121, v[180:181], s[10:11] offset:1024
	v_cvt_pk_bf16_f32 v182, v12, v13
	v_cvt_pk_bf16_f32 v183, v14, v15
	global_store_dwordx2 v121, v[182:183], s[10:11] offset:1536
	v_mul_f32_e32 v192, v1, v1
	v_mul_f32_e32 v193, v3, v3
	v_mul_f32_e32 v194, v5, v5
	v_mul_f32_e32 v195, v7, v7
	v_mul_f32_e32 v196, v9, v9
	v_mul_f32_e32 v197, v11, v11
	v_pk_mul_f32 v[198:199], v[14:15], v[14:15]
	v_pk_mul_f32 v[200:201], v[12:13], v[12:13]
	v_fmac_f32_e32 v192, v0, v0
	v_fmac_f32_e32 v193, v2, v2
	v_fmac_f32_e32 v194, v4, v4
	v_fmac_f32_e32 v195, v6, v6
	v_fmac_f32_e32 v196, v8, v8
	v_fmac_f32_e32 v197, v10, v10
	v_add_f32_e32 v202, v201, v200
	v_add_f32_e32 v203, v198, v199
	v_add_f32_e32 v192, v192, v193
	v_add_f32_e32 v193, v194, v195
	v_add_f32_e32 v194, v196, v197
	v_add_f32_e32 v192, v192, v193
	v_add_f32_e32 v202, v202, v203
	v_add_f32_e32 v193, v192, v194
	v_add_f32_e32 v202, v193, v202
	s_nop 1
	v_add_f32_dpp v202, v202, v202 quad_perm:[1,0,3,2] row_mask:0xf bank_mask:0xf bound_ctrl:1
	s_nop 1
	v_add_f32_dpp v202, v202, v202 quad_perm:[2,3,0,1] row_mask:0xf bank_mask:0xf bound_ctrl:1
	s_nop 1
	v_add_f32_dpp v202, v202, v202 row_half_mirror row_mask:0xf bank_mask:0xf bound_ctrl:1
	s_nop 1
	v_add_f32_dpp v202, v202, v202 row_mirror row_mask:0xf bank_mask:0xf bound_ctrl:1
	s_nop 1
	v_readlane_b32 s14, v202, 16
	v_readlane_b32 s15, v202, 48
	v_readlane_b32 s18, v202, 0
	v_readlane_b32 s19, v202, 32
	s_nop 1
	v_mov_b32_e32 v202, s14
	v_mov_b32_e32 v203, s15
	v_pk_add_f32 v[202:203], s[18:19], v[202:203]
	s_nop 0
	v_add_f32_e32 v202, v202, v203
	v_fmamk_f32 v202, v202, 0x3a800000, v116
	v_mul_f32_e32 v203, 0x4f800000, v202
	v_cmp_gt_f32_e32 vcc, s3, v202
	s_nop 1
	v_cndmask_b32_e32 v202, v202, v203, vcc
	v_sqrt_f32_e32 v203, v202
	s_nop 0
	v_add_u32_e32 v204, -1, v203
	v_add_u32_e32 v205, 1, v203
	v_fma_f32 v206, -v204, v203, v202
	v_fma_f32 v207, -v205, v203, v202
	v_cmp_ge_f32_e64 s[20:21], 0, v206
	s_nop 1
	v_cndmask_b32_e64 v203, v203, v204, s[20:21]
	v_cmp_lt_f32_e64 s[20:21], 0, v207
	s_nop 1
	v_cndmask_b32_e64 v203, v203, v205, s[20:21]
	v_mul_f32_e32 v204, 0x37800000, v203
	v_cndmask_b32_e32 v203, v203, v204, vcc
	v_cmp_class_f32_e32 vcc, v202, v117
	s_nop 1
	v_cndmask_b32_e32 v204, v203, v202, vcc
	v_div_scale_f32 v205, s[20:21], v204, v204, 1.0
	v_rcp_f32_e32 v206, v205
	v_div_scale_f32 v207, vcc, 1.0, v204, 1.0
	s_nop 0
	v_fma_f32 v208, -v205, v206, 1.0
	v_fmac_f32_e32 v206, v208, v206
	v_mul_f32_e32 v208, v207, v206
	v_fma_f32 v209, -v205, v208, v207
	v_fmac_f32_e32 v208, v209, v206
	v_fma_f32 v205, -v205, v208, v207
	v_div_fmas_f32 v205, v205, v206, v208
	v_div_fixup_f32 v210, v205, v204, 1.0
	v_pk_add_f32 v[16:17], v[16:17], 1.0 op_sel_hi:[1,0]
	v_pk_add_f32 v[18:19], v[18:19], 1.0 op_sel_hi:[1,0]
	v_pk_mul_f32 v[16:17], v[100:101], v[16:17]
	v_pk_mul_f32 v[18:19], v[102:103], v[18:19]
	v_pk_mul_f32 v[0:1], v[0:1], v[210:211] op_sel_hi:[1,0]
	v_pk_mul_f32 v[2:3], v[2:3], v[210:211] op_sel_hi:[1,0]
	v_pk_fma_f32 v[0:1], v[16:17], v[0:1], v[32:33]
	v_pk_fma_f32 v[2:3], v[18:19], v[2:3], v[34:35]
	v_cvt_pk_bf16_f32 v184, v0, v1
	v_cvt_pk_bf16_f32 v185, v2, v3
	global_store_dwordx2 v121, v[184:185], s[12:13]
	v_pk_add_f32 v[20:21], v[20:21], 1.0 op_sel_hi:[1,0]
	v_pk_add_f32 v[22:23], v[22:23], 1.0 op_sel_hi:[1,0]
	v_pk_mul_f32 v[20:21], v[104:105], v[20:21]
	v_pk_mul_f32 v[22:23], v[106:107], v[22:23]
	v_pk_mul_f32 v[4:5], v[4:5], v[210:211] op_sel_hi:[1,0]
	v_pk_mul_f32 v[6:7], v[6:7], v[210:211] op_sel_hi:[1,0]
	v_pk_fma_f32 v[4:5], v[20:21], v[4:5], v[36:37]
	v_pk_fma_f32 v[6:7], v[22:23], v[6:7], v[38:39]
	v_cvt_pk_bf16_f32 v186, v4, v5
	v_cvt_pk_bf16_f32 v187, v6, v7
	global_store_dwordx2 v121, v[186:187], s[12:13] offset:512
	v_pk_add_f32 v[24:25], v[24:25], 1.0 op_sel_hi:[1,0]
	v_pk_add_f32 v[26:27], v[26:27], 1.0 op_sel_hi:[1,0]
	v_pk_mul_f32 v[24:25], v[108:109], v[24:25]
	v_pk_mul_f32 v[26:27], v[110:111], v[26:27]
	v_pk_mul_f32 v[8:9], v[8:9], v[210:211] op_sel_hi:[1,0]
	v_pk_mul_f32 v[10:11], v[10:11], v[210:211] op_sel_hi:[1,0]
	v_pk_fma_f32 v[8:9], v[24:25], v[8:9], v[40:41]
	v_pk_fma_f32 v[10:11], v[26:27], v[10:11], v[42:43]
	v_cvt_pk_bf16_f32 v188, v8, v9
	v_cvt_pk_bf16_f32 v189, v10, v11
	global_store_dwordx2 v121, v[188:189], s[12:13] offset:1024
	v_pk_add_f32 v[28:29], v[28:29], 1.0 op_sel_hi:[1,0]
	v_pk_add_f32 v[30:31], v[30:31], 1.0 op_sel_hi:[1,0]
	v_pk_mul_f32 v[28:29], v[112:113], v[28:29]
	v_pk_mul_f32 v[30:31], v[114:115], v[30:31]
	v_pk_mul_f32 v[12:13], v[12:13], v[210:211] op_sel_hi:[1,0]
	v_pk_mul_f32 v[14:15], v[14:15], v[210:211] op_sel_hi:[1,0]
	v_pk_fma_f32 v[12:13], v[28:29], v[12:13], v[44:45]
	v_pk_fma_f32 v[14:15], v[30:31], v[14:15], v[46:47]
	v_cvt_pk_bf16_f32 v190, v12, v13
	v_cvt_pk_bf16_f32 v191, v14, v15
	global_store_dwordx2 v121, v[190:191], s[12:13] offset:1536
